# split packed fp32 VOP3P ops (v_pk_mul/add/fma_f32) into scalar pairs in the attention chunk loop and RG-LRU loop (asm guide 7.5)
# speedup vs baseline: 1.0025x; 1.0025x over previous
; __device__ __forceinline__ void rglru_item(const Ptrs& P, unsigned char* lds, int b, int n, int tid) {
;     ...
; #pragma unroll
;             for (int k = 0; k < 4; ++k) { const float m = (t0 + tt - 3 + k) >= 0 ? 1.f : 0.f;
;                 float cwk[16];
; #pragma unroll
;                 for (int e = 0; e < 16; e += 4) { const f32x4 c = *(const f32x4*)(P.conv_w + k * 2048 + cg0 + e); cwk[e] = c[0]; cwk[e + 1] = c[1]; cwk[e + 2] = c[2]; cwk[e + 3] = c[3]; }
;                 const u32x4 xa = xr[k][0], xb2 = xr[k][1];
;                 const float xv[16] = {bflo(xa.x), bfhi(xa.x), bflo(xa.y), bfhi(xa.y), bflo(xa.z), bfhi(xa.z), bflo(xa.w), bfhi(xa.w),
;                                       bflo(xb2.x), bfhi(xb2.x), bflo(xb2.y), bfhi(xb2.y), bflo(xb2.z), bfhi(xb2.z), bflo(xb2.w), bfhi(xb2.w)};
; #pragma unroll
;                 for (int e = 0; e < 16; ++e) xc[e] += (cwk[e] * m) * xv[e]; }
.LBB0_454:
	global_load_dwordx4 v[130:133], v[78:79], off
	global_load_dwordx4 v[134:137], v[80:81], off
	global_load_dwordx4 v[138:141], v[82:83], off
	global_load_dwordx4 v[142:145], v[78:79], off offset:16
	global_load_dwordx4 v[146:149], v[80:81], off offset:16
	global_load_dwordx4 v[150:153], v[82:83], off offset:16
	global_load_dwordx4 v[154:157], v[76:77], off
	global_load_dwordx4 v[158:161], v[76:77], off offset:16
	global_load_dwordx4 v[162:165], v[84:85], off
	global_load_dwordx4 v[166:169], v[84:85], off offset:16
	global_load_dwordx4 v[170:173], v[78:79], off offset:32
	global_load_dwordx4 v[174:177], v[76:77], off offset:32
	global_load_dwordx4 v[178:181], v[76:77], off offset:48
	global_load_dwordx4 v[182:185], v[78:79], off offset:48
	global_load_dwordx4 v[190:193], v[80:81], off offset:32
	global_load_dwordx4 v[194:197], v[80:81], off offset:48
	global_load_dwordx4 v[68:71], v[82:83], off offset:48
	global_load_dwordx4 v[198:201], v[82:83], off offset:32
	global_load_dwordx4 v[64:67], v[84:85], off offset:48
	global_load_dwordx4 v[202:205], v[84:85], off offset:32
	s_lshl_b32 s4, s3, 6
	v_add_u32_e32 v128, s4, v93
	v_cmp_lt_u32_e64 s[0:1], 2, v128
	s_waitcnt vmcnt(26)
	v_lshlrev_b32_e32 v88, 16, v36
	v_and_b32_e32 v89, 0xffff0000, v36
	v_cndmask_b32_e64 v72, 0, 1.0, s[0:1]
	v_cmp_lt_u32_e64 s[0:1], 1, v128
	s_waitcnt vmcnt(24)
	v_lshlrev_b32_e32 v186, 16, v44
	v_and_b32_e32 v187, 0xffff0000, v44
	v_cndmask_b32_e64 v234, 0, 1.0, s[0:1]
	v_cmp_eq_u32_e64 s[0:1], 0, v128
	v_lshlrev_b32_e32 v212, 16, v37
	v_and_b32_e32 v213, 0xffff0000, v37
	v_lshlrev_b32_e32 v220, 16, v38
	v_and_b32_e32 v221, 0xffff0000, v38
	v_lshlrev_b32_e32 v228, 16, v39
	v_and_b32_e32 v229, 0xffff0000, v39
	v_cndmask_b32_e64 v236, 1.0, 0, s[0:1]
	s_waitcnt vmcnt(22)
	v_lshlrev_b32_e32 v208, 16, v52
	v_and_b32_e32 v209, 0xffff0000, v52
	v_lshlrev_b32_e32 v214, 16, v45
	v_and_b32_e32 v215, 0xffff0000, v45
	v_lshlrev_b32_e32 v222, 16, v46
	v_and_b32_e32 v223, 0xffff0000, v46
	v_lshlrev_b32_e32 v230, 16, v47
	v_and_b32_e32 v231, 0xffff0000, v47
	s_waitcnt vmcnt(20)
	v_lshlrev_b32_e32 v210, 16, v60
	v_and_b32_e32 v211, 0xffff0000, v60
	v_lshlrev_b32_e32 v216, 16, v53
	v_and_b32_e32 v217, 0xffff0000, v53
	v_lshlrev_b32_e32 v224, 16, v54
	v_and_b32_e32 v225, 0xffff0000, v54
	v_lshlrev_b32_e32 v232, 16, v55
	v_and_b32_e32 v233, 0xffff0000, v55
	v_lshlrev_b32_e32 v218, 16, v61
	v_and_b32_e32 v219, 0xffff0000, v61
	v_lshlrev_b32_e32 v226, 16, v62
	v_and_b32_e32 v227, 0xffff0000, v62
	s_cmpk_eq_i32 s3, 0x7f
	s_waitcnt vmcnt(19)
	v_mul_f32_e32 v130, v72, v130
	v_mul_f32_e32 v131, v72, v131
	s_waitcnt vmcnt(18)
	v_mul_f32_e32 v134, v234, v134
	v_mul_f32_e32 v135, v234, v135
	v_mul_f32_e32 v132, v72, v132
	v_mul_f32_e32 v133, v72, v133
	s_waitcnt vmcnt(16)
	v_mul_f32_e32 v142, v72, v142
	v_mul_f32_e32 v143, v72, v143
	v_mul_f32_e32 v144, v72, v144
	v_mul_f32_e32 v145, v72, v145
	v_mul_f32_e32 v138, v236, v138
	v_mul_f32_e32 v139, v236, v139
	s_waitcnt vmcnt(13)
	v_fma_f32 v88, v130, v88, v154
	v_fma_f32 v89, v131, v89, v155
	v_mul_f32_e32 v136, v234, v136
	v_mul_f32_e32 v137, v234, v137
	v_mul_f32_e32 v146, v234, v146
	v_mul_f32_e32 v147, v234, v147
	v_mul_f32_e32 v148, v234, v148
	v_mul_f32_e32 v149, v234, v149
	v_fma_f32 v130, v132, v212, v156
	v_fma_f32 v131, v133, v213, v157
	s_waitcnt vmcnt(12)
	v_fma_f32 v132, v142, v220, v158
	v_fma_f32 v133, v143, v221, v159
	v_fma_f32 v142, v144, v228, v160
	v_fma_f32 v143, v145, v229, v161
	v_fma_f32 v88, v134, v186, v88
	v_fma_f32 v89, v135, v187, v89
	v_mul_f32_e32 v140, v236, v140
	v_mul_f32_e32 v141, v236, v141
	v_mul_f32_e32 v150, v236, v150
	v_mul_f32_e32 v151, v236, v151
	v_mul_f32_e32 v152, v236, v152
	v_mul_f32_e32 v153, v236, v153
	v_fma_f32 v130, v136, v214, v130
	v_fma_f32 v131, v137, v215, v131
	v_fma_f32 v132, v146, v222, v132
	v_fma_f32 v133, v147, v223, v133
	v_fma_f32 v134, v148, v230, v142
	v_fma_f32 v135, v149, v231, v143
	v_fma_f32 v88, v138, v208, v88
	v_fma_f32 v89, v139, v209, v89
	v_fma_f32 v136, v140, v216, v130
	v_fma_f32 v137, v141, v217, v131
	v_fma_f32 v138, v150, v224, v132
	v_fma_f32 v139, v151, v225, v133
	v_fma_f32 v140, v152, v232, v134
	v_fma_f32 v141, v153, v233, v135
	s_waitcnt vmcnt(11)
	v_fma_f32 v130, v162, v210, v88
	v_fma_f32 v131, v163, v211, v89
	v_lshlrev_b32_e32 v88, 16, v63
	v_and_b32_e32 v89, 0xffff0000, v63
	v_fma_f32 v132, v164, v218, v136
	v_fma_f32 v133, v165, v219, v137
	s_waitcnt vmcnt(10)
	v_fma_f32 v134, v166, v226, v138
	v_fma_f32 v135, v167, v227, v139
	v_fma_f32 v136, v168, v88, v140
	v_fma_f32 v137, v169, v89, v141
	v_lshlrev_b32_e32 v88, 16, v32
	v_and_b32_e32 v89, 0xffff0000, v32
	s_waitcnt vmcnt(9)
; __device__ __forceinline__ unsigned cvt_pk_bf16(float lo, float hi) { unsigned r; asm volatile("v_cvt_pk_bf16_f32 %0, %1, %2" : "=v"(r) : "v"(lo), "v"(hi)); return r; }
; #define RG_LOAD(T0) do { _Pragma("unroll") for (int k = 0; k < 4; ++k) { int tk = (T0) + tt - 3 + k; tk = tk < 0 ? 0 : tk; const bf16_t* xp = P.XR + (rowb + tk) * 2048 + cg0; \
;             xr[k][0] = *(const u32x4*)xp; xr[k][1] = *(const u32x4*)(xp + 8); } } while (0)
; __device__ __forceinline__ void rglru_item(const Ptrs& P, unsigned char* lds, int b, int n, int tid) {
;     ...
;             for (int e = 0; e < 16; e += 4) { const f32x4 v = *(const f32x4*)(P.conv_b + cg0 + e); xc[e] = v[0]; xc[e + 1] = v[1]; xc[e + 2] = v[2]; xc[e + 3] = v[3]; }
; #pragma unroll
;             for (int k = 0; k < 4; ++k) { const float m = (t0 + tt - 3 + k) >= 0 ? 1.f : 0.f;
;                 float cwk[16];
; #pragma unroll
;                 for (int e = 0; e < 16; e += 4) { const f32x4 c = *(const f32x4*)(P.conv_w + k * 2048 + cg0 + e); cwk[e] = c[0]; cwk[e + 1] = c[1]; cwk[e + 2] = c[2]; cwk[e + 3] = c[3]; }
;                 const u32x4 xa = xr[k][0], xb2 = xr[k][1];
;                 const float xv[16] = {bflo(xa.x), bfhi(xa.x), bflo(xa.y), bfhi(xa.y), bflo(xa.z), bfhi(xa.z), bflo(xa.w), bfhi(xa.w),
;                                       bflo(xb2.x), bfhi(xb2.x), bflo(xb2.y), bfhi(xb2.y), bflo(xb2.z), bfhi(xb2.z), bflo(xb2.w), bfhi(xb2.w)};
; #pragma unroll
;                 for (int e = 0; e < 16; ++e) xc[e] += (cwk[e] * m) * xv[e]; }
; #pragma unroll
;             for (int e = 0; e < 16; e += 4) *(f32x4*)(XCf + tt * 128 + c0 + e) = (f32x4){xc[e], xc[e + 1], xc[e + 2], xc[e + 3]};
;             u32x4 w0, w1; w0.x = cvt_pk_bf16(xc[0], xc[1]); w0.y = cvt_pk_bf16(xc[2], xc[3]); w0.z = cvt_pk_bf16(xc[4], xc[5]); w0.w = cvt_pk_bf16(xc[6], xc[7]);
;             w1.x = cvt_pk_bf16(xc[8], xc[9]); w1.y = cvt_pk_bf16(xc[10], xc[11]); w1.z = cvt_pk_bf16(xc[12], xc[13]); w1.w = cvt_pk_bf16(xc[14], xc[15]);
;             *(u32x4*)(XCb + tt * 136 + c0) = w0; *(u32x4*)(XCb + tt * 136 + c0 + 8) = w1;
;             { const bf16_t* gp_ = P.RG + (rowb + t0 + tt) * 2048 + cg0; gc0 = *(const u32x4*)gp_; gc1 = *(const u32x4*)(gp_ + 8); }
;             if (chunk + 1 < T / 64) RG_LOAD(t0 + 64);
	v_mul_f32_e32 v138, v72, v170
	v_mul_f32_e32 v139, v72, v171
	s_waitcnt vmcnt(8)
	v_fma_f32 v88, v138, v88, v174
	v_fma_f32 v89, v139, v89, v175
	v_lshlrev_b32_e32 v138, 16, v40
	v_and_b32_e32 v139, 0xffff0000, v40
	s_waitcnt vmcnt(5)
	v_mul_f32_e32 v140, v234, v190
	v_mul_f32_e32 v141, v234, v191
	v_fma_f32 v88, v140, v138, v88
	v_fma_f32 v89, v141, v139, v89
	v_lshlrev_b32_e32 v138, 16, v48
	v_and_b32_e32 v139, 0xffff0000, v48
	s_waitcnt vmcnt(2)
	v_mul_f32_e32 v140, v236, v198
	v_mul_f32_e32 v141, v236, v199
	v_fma_f32 v88, v140, v138, v88
	v_fma_f32 v89, v141, v139, v89
	v_lshlrev_b32_e32 v138, 16, v56
	v_and_b32_e32 v139, 0xffff0000, v56
	s_waitcnt vmcnt(0)
	v_fma_f32 v138, v202, v138, v88
	v_fma_f32 v139, v203, v139, v89
	v_lshlrev_b32_e32 v88, 16, v33
	v_and_b32_e32 v89, 0xffff0000, v33
	v_mul_f32_e32 v140, v72, v172
	v_mul_f32_e32 v141, v72, v173
	v_fma_f32 v88, v140, v88, v176
	v_fma_f32 v89, v141, v89, v177
	v_lshlrev_b32_e32 v140, 16, v41
	v_and_b32_e32 v141, 0xffff0000, v41
	v_mul_f32_e32 v142, v234, v192
	v_mul_f32_e32 v143, v234, v193
	v_fma_f32 v88, v142, v140, v88
	v_fma_f32 v89, v143, v141, v89
	v_lshlrev_b32_e32 v140, 16, v49
	v_and_b32_e32 v141, 0xffff0000, v49
	v_mul_f32_e32 v142, v236, v200
	v_mul_f32_e32 v143, v236, v201
	v_fma_f32 v88, v142, v140, v88
	v_fma_f32 v89, v143, v141, v89
	v_lshlrev_b32_e32 v140, 16, v57
	v_and_b32_e32 v141, 0xffff0000, v57
	v_fma_f32 v140, v204, v140, v88
	v_fma_f32 v141, v205, v141, v89
	v_lshlrev_b32_e32 v88, 16, v34
	v_and_b32_e32 v89, 0xffff0000, v34
	v_mul_f32_e32 v142, v72, v182
	v_mul_f32_e32 v143, v72, v183
	v_fma_f32 v88, v142, v88, v178
	v_fma_f32 v89, v143, v89, v179
	v_lshlrev_b32_e32 v142, 16, v42
	v_and_b32_e32 v143, 0xffff0000, v42
	v_mul_f32_e32 v144, v234, v194
	v_mul_f32_e32 v145, v234, v195
	v_fma_f32 v88, v144, v142, v88
	v_fma_f32 v89, v145, v143, v89
	v_lshlrev_b32_e32 v142, 16, v50
	v_and_b32_e32 v143, 0xffff0000, v50
	v_mul_f32_e32 v68, v236, v68
	v_mul_f32_e32 v69, v236, v69
	v_fma_f32 v68, v68, v142, v88
	v_fma_f32 v69, v69, v143, v89
	v_lshlrev_b32_e32 v88, 16, v58
	v_and_b32_e32 v89, 0xffff0000, v58
	v_fma_f32 v64, v64, v88, v68
	v_fma_f32 v65, v65, v89, v69
	v_lshlrev_b32_e32 v68, 16, v35
	v_and_b32_e32 v69, 0xffff0000, v35
	v_mul_f32_e32 v88, v72, v184
	v_mul_f32_e32 v89, v72, v185
	v_fma_f32 v68, v88, v68, v180
	v_fma_f32 v69, v89, v69, v181
	v_lshlrev_b32_e32 v88, 16, v43
	v_and_b32_e32 v89, 0xffff0000, v43
	v_mul_f32_e32 v142, v234, v196
	v_mul_f32_e32 v143, v234, v197
	v_fma_f32 v68, v142, v88, v68
	v_fma_f32 v69, v143, v89, v69
	v_lshlrev_b32_e32 v88, 16, v51
	v_and_b32_e32 v89, 0xffff0000, v51
	v_mul_f32_e32 v70, v236, v70
	v_mul_f32_e32 v71, v236, v71
	v_fma_f32 v68, v70, v88, v68
	v_fma_f32 v69, v71, v89, v69
	v_lshlrev_b32_e32 v70, 16, v59
	v_and_b32_e32 v71, 0xffff0000, v59
	v_add_u32_e32 v72, s4, v94
	v_fma_f32 v66, v66, v70, v68
	v_fma_f32 v67, v67, v71, v69
	ds_write_b128 v95, v[130:133] offset:17408
	ds_write_b128 v95, v[134:137] offset:17424
	ds_write_b128 v95, v[138:141] offset:17440
	ds_write_b128 v95, v[64:67] offset:17456
	v_cvt_pk_bf16_f32 v130, v130, v131
	v_cvt_pk_bf16_f32 v131, v132, v133
	v_cvt_pk_bf16_f32 v132, v134, v135
	v_cvt_pk_bf16_f32 v133, v136, v137
	v_cvt_pk_bf16_f32 v134, v138, v139
	v_cvt_pk_bf16_f32 v135, v140, v141
	v_cvt_pk_bf16_f32 v136, v64, v65
	v_lshlrev_b64 v[64:65], 12, v[72:73]
	v_lshl_add_u64 v[88:89], v[86:87], 0, v[64:65]
	v_cvt_pk_bf16_f32 v137, v66, v67
	global_load_dwordx4 v[64:67], v[88:89], off offset:16
	global_load_dwordx4 v[68:71], v[88:89], off
	ds_write_b128 v123, v[130:133]
	ds_write_b128 v123, v[134:137] offset:16
	s_cbranch_scc1 .LBB0_456
	v_add_u32_e32 v56, 61, v128
	v_add_u32_e32 v72, s6, v56
	v_lshlrev_b64 v[32:33], 12, v[72:73]
	v_add_u32_e32 v72, s7, v56
	v_lshlrev_b64 v[40:41], 12, v[72:73]
	v_add_u32_e32 v72, s8, v56
	v_lshlrev_b64 v[48:49], 12, v[72:73]
	v_add_u32_e32 v72, s9, v56
	v_lshlrev_b64 v[56:57], 12, v[72:73]
	v_lshl_add_u64 v[36:37], v[74:75], 0, v[32:33]
	v_lshl_add_u64 v[44:45], v[74:75], 0, v[40:41]
	v_lshl_add_u64 v[52:53], v[74:75], 0, v[48:49]
	v_lshl_add_u64 v[60:61], v[74:75], 0, v[56:57]
	global_load_dwordx4 v[32:35], v[36:37], off offset:16
	s_nop 0
	global_load_dwordx4 v[36:39], v[36:37], off
	s_nop 0
	global_load_dwordx4 v[40:43], v[44:45], off offset:16
	s_nop 0
	global_load_dwordx4 v[44:47], v[44:45], off
	s_nop 0
	global_load_dwordx4 v[48:51], v[52:53], off offset:16
	s_nop 0
	global_load_dwordx4 v[52:55], v[52:53], off
	s_nop 0
	global_load_dwordx4 v[56:59], v[60:61], off offset:16
	s_nop 0
	global_load_dwordx4 v[60:63], v[60:61], off

; __global__ void __launch_bounds__(512, 2) mega_fwd(Args args) {
;     ...
;             for (;;) {
;                 __syncthreads();
;                 if (tid == 0) *(volatile int*)(lds + 147712) = (int)atomicAdd(ctl + 64 * b, 1u);
;                 __syncthreads();
;                 const int item = *(volatile int*)(lds + 147712);
.Lq_next:
	s_waitcnt vmcnt(32)
	s_mov_b64 s[12:13], exec
	s_and_b64 exec, exec, s[0:1]
	v_mov_b32_e32 v0, 0x24104
	ds_write_b32 v0, v254
	s_mov_b64 exec, s[12:13]
	v_mov_b32_e32 v0, 0x24104
	s_waitcnt lgkmcnt(0)
	s_barrier
	ds_read_b32 v0, v0
	s_waitcnt lgkmcnt(0)
	s_branch .Lq_have_item
	s_nop 0
	s_nop 0
	s_nop 0
	s_nop 0
	s_nop 0
	s_nop 0
	s_nop 0
	s_nop 0
	s_nop 0
	s_nop 0
	s_nop 0
	s_nop 0
	s_nop 0
	s_nop 0
	s_nop 0
	s_nop 0
	s_nop 0
	s_nop 0

; __device__ __forceinline__ unsigned cvt_pk_bf16(float lo, float hi) { unsigned r; asm volatile("v_cvt_pk_bf16_f32 %0, %1, %2" : "=v"(r) : "v"(lo), "v"(hi)); return r; }
; __device__ __forceinline__ f32x4 mfma16(bf16x8 a, bf16x8 b, f32x4 c) { const f32x4 r = __builtin_amdgcn_mfma_f32_16x16x32_bf16(a, b, c, 0, 0, 0); asm volatile("" :: "v"(a), "v"(b)); return r; }
; __device__ __forceinline__ float row16_sum(float v) { v += dpp_f<0x121>(v); v += dpp_f<0x122>(v); v += dpp_f<0x124>(v); v += dpp_f<0x128>(v); return v; }
; __device__ __forceinline__ float row16_max(float v) { v = fmaxf(v, dpp_f<0x121>(v)); v = fmaxf(v, dpp_f<0x122>(v)); v = fmaxf(v, dpp_f<0x124>(v)); v = fmaxf(v, dpp_f<0x128>(v)); return v; }
; __device__ __forceinline__ void attn_item(const Ptrs& P, unsigned char* lds, int b, int tq0, int tid) {
;     ...
; #pragma unroll
;         for (int k2 = 0; k2 < 2; ++k2) {
;             const int slot = slot0 + 32 * ck + 16 * k2 + r16; const bool valid = slot < nsel; const int idx = (int)sel[q * 256 + slot];
;             int dist = tq - idx; dist = dist > 128 ? 128 : dist; dist = dist < 0 ? 0 : dist;
;             const f32x4 bb = *(const f32x4*)(P.BT + dist * 16 + 4 * g);
;             const bf16_t* kp = stw + (16 * k2 + r16) * SP + 8 * g;
;             f32x4 a = {0.f, 0.f, 0.f, 0.f};
; #pragma unroll
;             for (int ks = 0; ks < 8; ++ks) a = mfma16(Af[ks], *(const bf16x8*)(kp + 32 * ks), a);
; #pragma unroll
;             for (int j = 0; j < 4; ++j) a[j] = valid ? a[j] * 0.0625f + bb[j] : -1e30f;
;             sc[k2] = a;
;         }
; #pragma unroll
;         for (int j = 0; j < 4; ++j) {
;             const float mn = fmaxf(mrun[j], row16_max(fmaxf(sc[0][j], sc[1][j])));
;             const float scale = __expf(mrun[j] - mn);
;             const float p0 = __expf(sc[0][j] - mn), p1 = __expf(sc[1][j] - mn);
;             lrun[j] = lrun[j] * scale + row16_sum(p0 + p1);
;             mrun[j] = mn;
; #pragma unroll
;             for (int dt = 0; dt < 16; ++dt) oacc[dt][j] *= scale;
;             Pw[(4 * g + j) * 40 + r16] = (bf16_t)(cvt_pk_bf16(p0, 0.f) & 0xffffu);
;             Pw[(4 * g + j) * 40 + 16 + r16] = (bf16_t)(cvt_pk_bf16(p1, 0.f) & 0xffffu);
.LBB0_926:
	s_nop 0
	s_nop 0
	s_nop 0
	v_add_u32_e32 v233, s13, v226
	s_waitcnt lgkmcnt(0)
	v_add_u32_e32 v164, 0x21100, v233
	ds_read_u16 v164, v164
	ds_read_b128 v[238:241], v231
	ds_read_b128 v[248:251], v231 offset:64
	v_cmp_gt_u32_e32 vcc, v227, v221
	v_add_u32_e32 v253, 16, v227
	s_waitcnt lgkmcnt(1)
	v_mfma_f32_16x16x32_bf16 v[242:245], v[0:3], v[238:241], 0
	ds_read_b128 v[238:241], v231 offset:128
	v_sub_u32_e32 v164, v220, v164
	v_med3_i32 v164, v164, 0, v215
	v_lshlrev_b32_e32 v164, 6, v164
	v_add_u32_e64 v192, v176, v164
	ds_read_b128 v[234:237], v192
	s_waitcnt lgkmcnt(2)
	v_mfma_f32_16x16x32_bf16 v[242:245], v[4:7], v[248:251], v[242:245]
	ds_read_b128 v[248:251], v231 offset:192
	s_waitcnt lgkmcnt(2)
	v_mfma_f32_16x16x32_bf16 v[242:245], v[8:11], v[238:241], v[242:245]
	ds_read_b128 v[238:241], v231 offset:256
	s_waitcnt lgkmcnt(1)
	s_add_i32 s13, s13, 64
	v_mfma_f32_16x16x32_bf16 v[242:245], v[12:15], v[248:251], v[242:245]
	ds_read_b128 v[248:251], v231 offset:320
	s_waitcnt lgkmcnt(1)
	v_add_u32_e32 v227, 32, v227
	v_mfma_f32_16x16x32_bf16 v[242:245], v[16:19], v[238:241], v[242:245]
	ds_read_b128 v[238:241], v231 offset:384
	s_waitcnt lgkmcnt(1)
	s_cmp_eq_u32 s13, 0
	v_mfma_f32_16x16x32_bf16 v[242:245], v[20:23], v[248:251], v[242:245]
	ds_read_b128 v[248:251], v231 offset:448
	s_waitcnt lgkmcnt(1)
	v_mfma_f32_16x16x32_bf16 v[242:245], v[24:27], v[238:241], v[242:245]
	ds_read_b128 v[238:241], v231 offset:8448
	s_waitcnt lgkmcnt(1)
	v_mfma_f32_16x16x32_bf16 v[242:245], v[28:31], v[248:251], v[242:245]
	ds_read_b128 v[248:251], v231 offset:8512
	s_nop 6
	v_fmamk_f32 v164, v242, 0x3d800000, v234
	v_cndmask_b32_e32 v246, v164, v216, vcc
	v_fmamk_f32 v164, v243, 0x3d800000, v235
	v_cndmask_b32_e32 v247, v164, v216, vcc
	v_fmamk_f32 v164, v244, 0x3d800000, v236
	v_cndmask_b32_e32 v193, v164, v216, vcc
	v_add_u32_e32 v164, 0x21120, v233
	ds_read_u16 v164, v164
	v_fmac_f32_e32 v237, 0x3d800000, v245
	v_cndmask_b32_e32 v192, v237, v216, vcc
	s_waitcnt lgkmcnt(2)
	v_mfma_f32_16x16x32_bf16 v[242:245], v[0:3], v[238:241], 0
	ds_read_b128 v[238:241], v231 offset:8576
	v_cmp_gt_u32_e32 vcc, v253, v221
	s_waitcnt lgkmcnt(1)
	v_sub_u32_e32 v164, v220, v164
	v_med3_i32 v164, v164, 0, v215
	v_lshlrev_b32_e32 v164, 6, v164
	v_add_u32_e64 v234, v176, v164
	ds_read_b128 v[234:237], v234
	v_mfma_f32_16x16x32_bf16 v[242:245], v[4:7], v[248:251], v[242:245]
	ds_read_b128 v[248:251], v231 offset:8640
	s_waitcnt lgkmcnt(2)
	v_mfma_f32_16x16x32_bf16 v[242:245], v[8:11], v[238:241], v[242:245]
	ds_read_b128 v[238:241], v231 offset:8704
	s_waitcnt lgkmcnt(1)
	v_mfma_f32_16x16x32_bf16 v[242:245], v[12:15], v[248:251], v[242:245]
	ds_read_b128 v[248:251], v231 offset:8768
	s_waitcnt lgkmcnt(1)
	v_mfma_f32_16x16x32_bf16 v[242:245], v[16:19], v[238:241], v[242:245]
	ds_read_b128 v[238:241], v231 offset:8832
	s_waitcnt lgkmcnt(1)
	v_mfma_f32_16x16x32_bf16 v[242:245], v[20:23], v[248:251], v[242:245]
	ds_read_b128 v[248:251], v231 offset:8896
	s_waitcnt lgkmcnt(1)
	v_mfma_f32_16x16x32_bf16 v[242:245], v[24:27], v[238:241], v[242:245]
	s_waitcnt lgkmcnt(0)
	v_mfma_f32_16x16x32_bf16 v[242:245], v[28:31], v[248:251], v[242:245]
	s_nop 7
	v_fmamk_f32 v164, v242, 0x3d800000, v234
	v_cndmask_b32_e32 v233, v164, v216, vcc
	v_fmamk_f32 v164, v243, 0x3d800000, v235
	v_cndmask_b32_e32 v238, v164, v216, vcc
	v_fmamk_f32 v164, v244, 0x3d800000, v236
	v_cndmask_b32_e32 v244, v164, v216, vcc
	v_max_f32_e32 v164, v246, v233
	v_fmac_f32_e32 v237, 0x3d800000, v245
	v_cndmask_b32_e32 v236, v237, v216, vcc
	v_mov_b32_dpp v234, v164 row_ror:1 row_mask:0xf bank_mask:0xf bound_ctrl:1
	v_max_f32_e32 v234, v234, v234
	v_max_f32_e32 v164, v164, v234
	s_nop 1
	v_mov_b32_dpp v234, v164 row_ror:2 row_mask:0xf bank_mask:0xf bound_ctrl:1
	v_max_f32_e32 v234, v234, v234
	v_max_f32_e32 v164, v164, v234
	s_nop 1
	v_mov_b32_dpp v234, v164 row_ror:4 row_mask:0xf bank_mask:0xf bound_ctrl:1
	v_max_f32_e32 v234, v234, v234
	v_max_f32_e32 v164, v164, v234
	s_nop 1
	v_mov_b32_dpp v234, v164 row_ror:8 row_mask:0xf bank_mask:0xf bound_ctrl:1
	v_max3_f32 v164, v161, v164, v234
	v_sub_f32_e32 v234, v246, v164
	v_sub_f32_e32 v233, v233, v164
	v_mul_f32_e32 v234, 0x3fb8aa3b, v234
	v_mul_f32_e32 v233, 0x3fb8aa3b, v233
	v_exp_f32_e32 v235, v234
	v_exp_f32_e32 v239, v233
	v_cvt_pk_bf16_f32 v233, v235, v165
	ds_write_b16 v223, v233
	v_cvt_pk_bf16_f32 v233, v239, v165
	ds_write_b16 v224, v233 offset:32
	v_max_f32_e32 v233, v247, v238
	v_sub_f32_e32 v161, v161, v164
	v_mul_f32_e32 v161, 0x3fb8aa3b, v161
	v_mov_b32_dpp v234, v233 row_ror:1 row_mask:0xf bank_mask:0xf bound_ctrl:1
	v_max_f32_e32 v234, v234, v234
	v_max_f32_e32 v233, v233, v234
	v_exp_f32_e32 v161, v161
	s_nop 0
	v_mov_b32_dpp v234, v233 row_ror:2 row_mask:0xf bank_mask:0xf bound_ctrl:1
	v_max_f32_e32 v234, v234, v234
	v_max_f32_e32 v233, v233, v234
	s_nop 1
	v_mov_b32_dpp v234, v233 row_ror:4 row_mask:0xf bank_mask:0xf bound_ctrl:1
	v_max_f32_e32 v234, v234, v234
	v_max_f32_e32 v233, v233, v234
	s_nop 1
	v_mov_b32_dpp v234, v233 row_ror:8 row_mask:0xf bank_mask:0xf bound_ctrl:1
	v_max3_f32 v233, v160, v233, v234
	v_sub_f32_e32 v234, v247, v233
	v_sub_f32_e32 v237, v238, v233
	v_mul_f32_e32 v234, 0x3fb8aa3b, v234
	v_mul_f32_e32 v237, 0x3fb8aa3b, v237
	v_exp_f32_e32 v234, v234
	v_exp_f32_e32 v238, v237
	v_sub_f32_e32 v160, v160, v233
	v_mul_f32_e32 v160, 0x3fb8aa3b, v160
	v_exp_f32_e32 v160, v160
	v_add_f32_e32 v240, v234, v238
	v_add_f32_e32 v241, v235, v239
	v_cvt_pk_bf16_f32 v234, v234, v165
	ds_write_b16 v223, v234 offset:80
	v_cvt_pk_bf16_f32 v234, v238, v165
	ds_write_b16 v224, v234 offset:112
	v_max_f32_e32 v234, v193, v244
; __device__ __forceinline__ unsigned cvt_pk_bf16(float lo, float hi) { unsigned r; asm volatile("v_cvt_pk_bf16_f32 %0, %1, %2" : "=v"(r) : "v"(lo), "v"(hi)); return r; }
; __device__ __forceinline__ float row16_sum(float v) { v += dpp_f<0x121>(v); v += dpp_f<0x122>(v); v += dpp_f<0x124>(v); v += dpp_f<0x128>(v); return v; }
; __device__ __forceinline__ float row16_max(float v) { v = fmaxf(v, dpp_f<0x121>(v)); v = fmaxf(v, dpp_f<0x122>(v)); v = fmaxf(v, dpp_f<0x124>(v)); v = fmaxf(v, dpp_f<0x128>(v)); return v; }
; __device__ __forceinline__ void attn_item(const Ptrs& P, unsigned char* lds, int b, int tq0, int tid) {
;     ...
;         for (int j = 0; j < 4; ++j) {
;             const float mn = fmaxf(mrun[j], row16_max(fmaxf(sc[0][j], sc[1][j])));
;             const float scale = __expf(mrun[j] - mn);
;             const float p0 = __expf(sc[0][j] - mn), p1 = __expf(sc[1][j] - mn);
;             lrun[j] = lrun[j] * scale + row16_sum(p0 + p1);
;             mrun[j] = mn;
; #pragma unroll
;             for (int dt = 0; dt < 16; ++dt) oacc[dt][j] *= scale;
;             Pw[(4 * g + j) * 40 + r16] = (bf16_t)(cvt_pk_bf16(p0, 0.f) & 0xffffu);
;             Pw[(4 * g + j) * 40 + 16 + r16] = (bf16_t)(cvt_pk_bf16(p1, 0.f) & 0xffffu);
;         }
	v_mov_b32_dpp v243, v241 row_ror:1 row_mask:0xf bank_mask:0xf bound_ctrl:1
	v_mov_b32_dpp v242, v240 row_ror:1 row_mask:0xf bank_mask:0xf bound_ctrl:1
	v_mov_b32_dpp v235, v234 row_ror:1 row_mask:0xf bank_mask:0xf bound_ctrl:1
	v_max_f32_e32 v235, v235, v235
	v_max_f32_e32 v234, v234, v235
	v_add_f32_e32 v240, v240, v242
	v_add_f32_e32 v241, v241, v243
	s_nop 0
	v_mov_b32_dpp v235, v234 row_ror:2 row_mask:0xf bank_mask:0xf bound_ctrl:1
	v_max_f32_e32 v235, v235, v235
	v_max_f32_e32 v234, v234, v235
	v_mov_b32_dpp v243, v241 row_ror:2 row_mask:0xf bank_mask:0xf bound_ctrl:1
	v_mov_b32_dpp v242, v240 row_ror:2 row_mask:0xf bank_mask:0xf bound_ctrl:1
	v_mov_b32_dpp v235, v234 row_ror:4 row_mask:0xf bank_mask:0xf bound_ctrl:1
	v_max_f32_e32 v235, v235, v235
	v_max_f32_e32 v234, v234, v235
	v_add_f32_e32 v240, v240, v242
	v_add_f32_e32 v241, v241, v243
	s_nop 0
	v_mov_b32_dpp v235, v234 row_ror:8 row_mask:0xf bank_mask:0xf bound_ctrl:1
	v_max3_f32 v234, v163, v234, v235
	v_sub_f32_e32 v163, v163, v234
	v_mul_f32_e32 v163, 0x3fb8aa3b, v163
	v_exp_f32_e32 v239, v163
	v_sub_f32_e32 v163, v193, v234
	v_mul_f32_e32 v163, 0x3fb8aa3b, v163
	v_sub_f32_e32 v193, v244, v234
	v_exp_f32_e32 v163, v163
	v_mul_f32_e32 v193, 0x3fb8aa3b, v193
	v_cvt_pk_bf16_f32 v235, v163, v165
	v_exp_f32_e32 v193, v193
	ds_write_b16 v223, v235 offset:160
	v_cvt_pk_bf16_f32 v235, v193, v165
	ds_write_b16 v224, v235 offset:192
	v_max_f32_e32 v235, v192, v236
	v_mov_b32_dpp v243, v241 row_ror:4 row_mask:0xf bank_mask:0xf bound_ctrl:1
	v_mov_b32_dpp v242, v240 row_ror:4 row_mask:0xf bank_mask:0xf bound_ctrl:1
	v_mov_b32_dpp v237, v235 row_ror:1 row_mask:0xf bank_mask:0xf bound_ctrl:1
	v_max_f32_e32 v237, v237, v237
	v_max_f32_e32 v235, v235, v237
	v_add_f32_e32 v240, v240, v242
	v_add_f32_e32 v241, v241, v243
	s_nop 0
	v_mov_b32_dpp v237, v235 row_ror:2 row_mask:0xf bank_mask:0xf bound_ctrl:1
	v_max_f32_e32 v237, v237, v237
	v_max_f32_e32 v235, v235, v237
	v_mov_b32_dpp v243, v241 row_ror:8 row_mask:0xf bank_mask:0xf bound_ctrl:1
	v_mov_b32_dpp v242, v240 row_ror:8 row_mask:0xf bank_mask:0xf bound_ctrl:1
	v_mov_b32_dpp v237, v235 row_ror:4 row_mask:0xf bank_mask:0xf bound_ctrl:1
	v_max_f32_e32 v237, v237, v237
	v_max_f32_e32 v235, v235, v237
	v_add_f32_e32 v240, v240, v242
	v_add_f32_e32 v241, v241, v243
	s_nop 0
	v_mov_b32_dpp v237, v235 row_ror:8 row_mask:0xf bank_mask:0xf bound_ctrl:1
	v_max3_f32 v235, v162, v235, v237
	v_sub_f32_e32 v162, v162, v235
	v_mul_f32_e32 v162, 0x3fb8aa3b, v162
	v_exp_f32_e32 v238, v162
	v_sub_f32_e32 v162, v192, v235
	v_sub_f32_e32 v192, v236, v235
	v_mul_f32_e32 v162, 0x3fb8aa3b, v162
	v_mul_f32_e32 v192, 0x3fb8aa3b, v192
	v_exp_f32_e32 v162, v162
	v_exp_f32_e32 v192, v192
	v_fma_f32 v190, v190, v160, v240
	v_fma_f32 v191, v191, v161, v241
	v_add_f32_e32 v236, v162, v192
	v_add_f32_e32 v237, v163, v193
	s_nop 1
	v_mov_b32_dpp v241, v237 row_ror:1 row_mask:0xf bank_mask:0xf bound_ctrl:1
	v_mov_b32_dpp v240, v236 row_ror:1 row_mask:0xf bank_mask:0xf bound_ctrl:1
	v_add_f32_e32 v236, v236, v240
	v_add_f32_e32 v237, v237, v241
	s_nop 1
	v_mov_b32_dpp v241, v237 row_ror:2 row_mask:0xf bank_mask:0xf bound_ctrl:1
	v_mov_b32_dpp v240, v236 row_ror:2 row_mask:0xf bank_mask:0xf bound_ctrl:1
	v_add_f32_e32 v236, v236, v240
	v_add_f32_e32 v237, v237, v241
	s_nop 1
	v_mov_b32_dpp v241, v237 row_ror:4 row_mask:0xf bank_mask:0xf bound_ctrl:1
	v_mov_b32_dpp v240, v236 row_ror:4 row_mask:0xf bank_mask:0xf bound_ctrl:1
	v_add_f32_e32 v236, v236, v240
	v_add_f32_e32 v237, v237, v241
	s_nop 1
	v_mov_b32_dpp v241, v237 row_ror:8 row_mask:0xf bank_mask:0xf bound_ctrl:1
	v_mov_b32_dpp v240, v236 row_ror:8 row_mask:0xf bank_mask:0xf bound_ctrl:1
	v_add_f32_e32 v236, v236, v240
	v_add_f32_e32 v237, v237, v241
	s_nop 0
	v_fma_f32 v186, v186, v238, v236
	v_fma_f32 v187, v187, v239, v237
	v_mov_b32_e32 v236, v239
	v_mov_b32_e32 v239, v160
	v_cvt_pk_bf16_f32 v160, v162, v165
	ds_write_b16 v223, v160 offset:240
	v_cvt_pk_bf16_f32 v160, v192, v165
	ds_write_b16 v224, v160 offset:272
	s_waitcnt lgkmcnt(0)
; __device__ __forceinline__ unsigned cvt_pk_bf16(float lo, float hi) { unsigned r; asm volatile("v_cvt_pk_bf16_f32 %0, %1, %2" : "=v"(r) : "v"(lo), "v"(hi)); return r; }
; __device__ __forceinline__ f32x4 mfma16(bf16x8 a, bf16x8 b, f32x4 c) { const f32x4 r = __builtin_amdgcn_mfma_f32_16x16x32_bf16(a, b, c, 0, 0, 0); asm volatile("" :: "v"(a), "v"(b)); return r; }
; __device__ __forceinline__ void attn_item(const Ptrs& P, unsigned char* lds, int b, int tq0, int tid) {
;     ...
;             for (int dt = 0; dt < 16; ++dt) oacc[dt][j] *= scale;
;             Pw[(4 * g + j) * 40 + r16] = (bf16_t)(cvt_pk_bf16(p0, 0.f) & 0xffffu);
;             Pw[(4 * g + j) * 40 + 16 + r16] = (bf16_t)(cvt_pk_bf16(p1, 0.f) & 0xffffu);
;         }
;         asm volatile("s_waitcnt lgkmcnt(0)" ::: "memory");
;         const bf16x8 Ap = *(const bf16x8*)(Pw + r16 * 40 + 8 * g);
; #pragma unroll
;         for (int hh = 0; hh < 4; ++hh) {
;             s16x4 r[8];
;             if (hh == 0) TR8(r, 0); else if (hh == 1) TR8(r, 128); else if (hh == 2) TR8(r, 256); else TR8(r, 384);
; #pragma unroll
;             for (int dt = 0; dt < 4; ++dt) { bf16x8 Bv; Bv[0] = r[2 * dt][0]; Bv[1] = r[2 * dt][1]; Bv[2] = r[2 * dt][2]; Bv[3] = r[2 * dt][3];
;                 Bv[4] = r[2 * dt + 1][0]; Bv[5] = r[2 * dt + 1][1]; Bv[6] = r[2 * dt + 1][2]; Bv[7] = r[2 * dt + 1][3];
;                 oacc[4 * hh + dt] = mfma16(Ap, Bv, oacc[4 * hh + dt]); }
;         }
	v_mov_b32_e32 v237, v238
	v_mov_b32_e32 v238, v161
	ds_read_b128 v[160:163], v232
	v_mul_f32_e32 v110, v110, v236
	v_mul_f32_e32 v111, v111, v237
	v_mul_f32_e32 v108, v108, v238
	v_mul_f32_e32 v109, v109, v239
	v_mul_f32_e32 v102, v102, v236
	v_mul_f32_e32 v103, v103, v237
	v_mul_f32_e32 v100, v100, v238
	v_mul_f32_e32 v101, v101, v239
	v_mul_f32_e32 v86, v86, v236
	v_mul_f32_e32 v87, v87, v237
	v_mul_f32_e32 v84, v84, v238
	v_mul_f32_e32 v85, v85, v239
	v_mul_f32_e32 v70, v70, v236
	v_mul_f32_e32 v71, v71, v237
	v_mul_f32_e32 v68, v68, v238
	v_mul_f32_e32 v69, v69, v239
	v_mul_f32_e32 v50, v50, v236
	v_mul_f32_e32 v51, v51, v237
	v_mul_f32_e32 v48, v48, v238
	v_mul_f32_e32 v49, v49, v239
	v_mul_f32_e32 v42, v42, v236
	v_mul_f32_e32 v43, v43, v237
	v_mul_f32_e32 v40, v40, v238
	v_mul_f32_e32 v41, v41, v239
	v_mul_f32_e32 v38, v38, v236
	v_mul_f32_e32 v39, v39, v237
	v_mul_f32_e32 v36, v36, v238
	v_mul_f32_e32 v37, v37, v239
	v_mul_f32_e32 v34, v34, v236
	v_mul_f32_e32 v35, v35, v237
	v_mul_f32_e32 v32, v32, v238
	v_mul_f32_e32 v33, v33, v239
	v_mul_f32_e32 v150, v150, v236
	v_mul_f32_e32 v151, v151, v237
	v_mul_f32_e32 v148, v148, v238
	v_mul_f32_e32 v149, v149, v239
	v_mul_f32_e32 v138, v138, v236
	v_mul_f32_e32 v139, v139, v237
	v_mul_f32_e32 v136, v136, v238
	v_mul_f32_e32 v137, v137, v239
	v_mul_f32_e32 v126, v126, v236
	v_mul_f32_e32 v127, v127, v237
	v_mul_f32_e32 v124, v124, v238
	v_mul_f32_e32 v125, v125, v239
	v_mul_f32_e32 v114, v114, v236
	v_mul_f32_e32 v115, v115, v237
	v_mul_f32_e32 v112, v112, v238
	v_mul_f32_e32 v113, v113, v239
	v_mul_f32_e32 v106, v106, v236
	v_mul_f32_e32 v107, v107, v237
	v_mul_f32_e32 v104, v104, v238
	v_mul_f32_e32 v105, v105, v239
	v_mul_f32_e32 v98, v98, v236
	v_mul_f32_e32 v99, v99, v237
	v_mul_f32_e32 v96, v96, v238
	v_mul_f32_e32 v97, v97, v239
	v_mul_f32_e32 v82, v82, v236
	v_mul_f32_e32 v83, v83, v237
	v_mul_f32_e32 v80, v80, v238
	v_mul_f32_e32 v81, v81, v239
	v_mul_f32_e32 v46, v46, v236
	v_mul_f32_e32 v47, v47, v237
	v_mul_f32_e32 v44, v44, v238
	v_mul_f32_e32 v45, v45, v239
	ds_read_b64_tr_b16 v[236:237], v222 offset:0+0
	ds_read_b64_tr_b16 v[238:239], v222 offset:0+2112
	ds_read_b64_tr_b16 v[240:241], v222 offset:0+32
	ds_read_b64_tr_b16 v[242:243], v222 offset:0+2144
	ds_read_b64_tr_b16 v[244:245], v222 offset:0+64
	ds_read_b64_tr_b16 v[246:247], v222 offset:0+2176
	ds_read_b64_tr_b16 v[248:249], v222 offset:0+96
	ds_read_b64_tr_b16 v[250:251], v222 offset:0+2208
	s_waitcnt lgkmcnt(0)
	s_waitcnt lgkmcnt(0)
	v_mfma_f32_16x16x32_bf16 v[108:111], v[160:163], v[236:239], v[108:111]
	v_mfma_f32_16x16x32_bf16 v[100:103], v[160:163], v[240:243], v[100:103]
	v_mfma_f32_16x16x32_bf16 v[84:87], v[160:163], v[244:247], v[84:87]
	v_mfma_f32_16x16x32_bf16 v[68:71], v[160:163], v[248:251], v[68:71]
	ds_read_b64_tr_b16 v[236:237], v222 offset:128+0
	ds_read_b64_tr_b16 v[238:239], v222 offset:128+2112
	ds_read_b64_tr_b16 v[240:241], v222 offset:128+32
	ds_read_b64_tr_b16 v[242:243], v222 offset:128+2144
	ds_read_b64_tr_b16 v[244:245], v222 offset:128+64
	ds_read_b64_tr_b16 v[246:247], v222 offset:128+2176
	ds_read_b64_tr_b16 v[248:249], v222 offset:128+96
	ds_read_b64_tr_b16 v[250:251], v222 offset:128+2208
	s_waitcnt lgkmcnt(0)
	s_nop 0
	v_mfma_f32_16x16x32_bf16 v[48:51], v[160:163], v[236:239], v[48:51]
	v_mfma_f32_16x16x32_bf16 v[40:43], v[160:163], v[240:243], v[40:43]
	v_mfma_f32_16x16x32_bf16 v[36:39], v[160:163], v[244:247], v[36:39]
	v_mfma_f32_16x16x32_bf16 v[32:35], v[160:163], v[248:251], v[32:35]
	ds_read_b64_tr_b16 v[236:237], v222 offset:256+0
	ds_read_b64_tr_b16 v[238:239], v222 offset:256+2112
	ds_read_b64_tr_b16 v[240:241], v222 offset:256+32
	ds_read_b64_tr_b16 v[242:243], v222 offset:256+2144
	ds_read_b64_tr_b16 v[244:245], v222 offset:256+64
	ds_read_b64_tr_b16 v[246:247], v222 offset:256+2176
	ds_read_b64_tr_b16 v[248:249], v222 offset:256+96
	ds_read_b64_tr_b16 v[250:251], v222 offset:256+2208
	s_waitcnt lgkmcnt(0)
	s_nop 0
	v_mfma_f32_16x16x32_bf16 v[148:151], v[160:163], v[236:239], v[148:151]
	v_mfma_f32_16x16x32_bf16 v[136:139], v[160:163], v[240:243], v[136:139]
	v_mfma_f32_16x16x32_bf16 v[124:127], v[160:163], v[244:247], v[124:127]
	v_mfma_f32_16x16x32_bf16 v[112:115], v[160:163], v[248:251], v[112:115]
	ds_read_b64_tr_b16 v[236:237], v222 offset:384+0
	ds_read_b64_tr_b16 v[238:239], v222 offset:384+2112
	ds_read_b64_tr_b16 v[240:241], v222 offset:384+32
	ds_read_b64_tr_b16 v[242:243], v222 offset:384+2144
	ds_read_b64_tr_b16 v[244:245], v222 offset:384+64
	ds_read_b64_tr_b16 v[246:247], v222 offset:384+2176
	ds_read_b64_tr_b16 v[248:249], v222 offset:384+96
	ds_read_b64_tr_b16 v[250:251], v222 offset:384+2208
	s_waitcnt lgkmcnt(0)
	s_nop 0
	v_mfma_f32_16x16x32_bf16 v[104:107], v[160:163], v[236:239], v[104:107]
	v_mfma_f32_16x16x32_bf16 v[96:99], v[160:163], v[240:243], v[96:99]
	v_mfma_f32_16x16x32_bf16 v[80:83], v[160:163], v[244:247], v[80:83]
	v_mfma_f32_16x16x32_bf16 v[44:47], v[160:163], v[248:251], v[44:47]
	s_cbranch_scc1 .LBB0_928
	v_mov_b32_e32 v162, v235
	v_mov_b32_e32 v163, v234
	v_mov_b32_e32 v160, v233
	v_mov_b32_e32 v161, v164
	s_branch .LBB0_924
